# attention softmax: subtract-max and log2e scale folded into one fused multiply-add per score
# baseline (speedup 1.0000x reference)
.LBB0_505:
	s_ashr_i32 s9, s7, 31
	s_xor_b32 s8, s8, s9
	s_sub_i32 s8, s8, s9
	s_mul_i32 s9, s8, s19
	s_sub_i32 s9, s6, s9
	s_lshl_b32 s9, s9, 3
	s_and_b32 s6, s59, 48
	s_max_i32 s10, s9, 4
	v_sub_u32_e64 v64, s6, 8 clamp
	s_add_i32 s10, s10, -4
	s_and_b32 s60, s7, 7
	s_lshl_b32 s11, s8, s52
	v_min_u32_e32 v168, 32, v64
	s_min_i32 s10, s10, s53
	s_add_i32 s7, s9, s21
	s_lshl_b32 s9, s7, 6
	s_add_i32 s9, s9, s11
	s_or_b32 s9, s9, s6
	v_or_b32_e32 v142, s9, v139
	v_ashrrev_i32_e32 v143, 31, v142
	v_readlane_b32 s28, v250, 8
	v_lshlrev_b64 v[64:65], 11, v[142:143]
	v_readlane_b32 s29, v250, 9
	s_lshl_b32 s36, s60, 7
	s_max_i32 s8, s7, 4
	v_lshl_add_u64 v[64:65], s[28:29], 0, v[64:65]
	v_lshl_add_u64 v[64:65], v[64:65], 0, s[36:37]
	v_lshl_add_u64 v[68:69], v[64:65], 0, v[144:145]
	global_load_dwordx4 v[64:67], v[68:69], off
	global_load_dwordx4 v[128:131], v[68:69], off offset:64
	s_add_i32 s8, s8, -4
	s_min_i32 s8, s8, s54
	s_sub_i32 s36, s8, s10
	v_lshl_add_u32 v72, s36, 12, v160
	v_add_u32_e32 v169, v72, v161
	s_waitcnt lgkmcnt(0)
	s_barrier
	v_add_u32_e32 v170, v72, v162
	ds_read_b128 v[196:199], v169
	ds_read_b128 v[200:203], v170
	ds_read_b128 v[204:207], v169 offset:2048
	ds_read_b128 v[208:211], v170 offset:2048
	ds_read_b128 v[212:215], v169 offset:4096
	ds_read_b128 v[216:219], v170 offset:4096
	s_mul_i32 s9, s60, 0x780
	s_sub_i32 s7, s8, s7
	s_add_i32 s9, s9, 0
	s_mulk_i32 s7, 0x7c
	s_add_i32 s61, s9, s7
	s_add_i32 s61, s61, 0x1f400
	v_or_b32_e32 v189, s6, v139
	s_waitcnt vmcnt(1) lgkmcnt(4)
	v_mfma_f32_16x16x32_bf16 v[124:127], v[196:199], v[64:67], 0
	s_waitcnt vmcnt(0)
	v_mfma_f32_16x16x32_bf16 v[124:127], v[200:203], v[128:131], v[124:127]
	ds_read_b128 v[196:199], v169 offset:6144
	ds_read_b128 v[200:203], v170 offset:6144
	s_waitcnt lgkmcnt(4)
	v_mfma_f32_16x16x32_bf16 v[120:123], v[204:207], v[64:67], 0
	v_mfma_f32_16x16x32_bf16 v[120:123], v[208:211], v[128:131], v[120:123]
	ds_read_b128 v[204:207], v169 offset:8192
	ds_read_b128 v[208:211], v170 offset:8192
	s_waitcnt lgkmcnt(4)
	v_mfma_f32_16x16x32_bf16 v[116:119], v[212:215], v[64:67], 0
	v_mfma_f32_16x16x32_bf16 v[116:119], v[216:219], v[128:131], v[116:119]
	ds_read_b128 v[212:215], v169 offset:10240
	ds_read_b128 v[216:219], v170 offset:10240
	s_waitcnt lgkmcnt(4)
	v_mfma_f32_16x16x32_bf16 v[112:115], v[196:199], v[64:67], 0
	v_mfma_f32_16x16x32_bf16 v[112:115], v[200:203], v[128:131], v[112:115]
	ds_read_b128 v[196:199], v169 offset:12288
	ds_read_b128 v[200:203], v170 offset:12288
	s_waitcnt lgkmcnt(4)
	v_mfma_f32_16x16x32_bf16 v[108:111], v[204:207], v[64:67], 0
	v_mfma_f32_16x16x32_bf16 v[108:111], v[208:211], v[128:131], v[108:111]
	ds_read_b128 v[204:207], v169 offset:14336
	ds_read_b128 v[208:211], v170 offset:14336
	s_waitcnt lgkmcnt(4)
	v_mfma_f32_16x16x32_bf16 v[104:107], v[212:215], v[64:67], 0
	v_mfma_f32_16x16x32_bf16 v[104:107], v[216:219], v[128:131], v[104:107]
	ds_read_b128 v[212:215], v169 offset:16384
	ds_read_b128 v[216:219], v170 offset:16384
	s_waitcnt lgkmcnt(4)
	v_mfma_f32_16x16x32_bf16 v[100:103], v[196:199], v[64:67], 0
	v_mfma_f32_16x16x32_bf16 v[100:103], v[200:203], v[128:131], v[100:103]
	ds_read_b128 v[196:199], v169 offset:18432
	ds_read_b128 v[200:203], v170 offset:18432
	s_waitcnt lgkmcnt(4)
	v_mfma_f32_16x16x32_bf16 v[96:99], v[204:207], v[64:67], 0
	v_mfma_f32_16x16x32_bf16 v[96:99], v[208:211], v[128:131], v[96:99]
	ds_read_b128 v[204:207], v169 offset:20480
	ds_read_b128 v[208:211], v170 offset:20480
	s_waitcnt lgkmcnt(4)
	v_mfma_f32_16x16x32_bf16 v[92:95], v[212:215], v[64:67], 0
	v_mfma_f32_16x16x32_bf16 v[92:95], v[216:219], v[128:131], v[92:95]
	ds_read_b128 v[212:215], v169 offset:22528
	ds_read_b128 v[216:219], v170 offset:22528
	s_waitcnt lgkmcnt(4)
	v_mfma_f32_16x16x32_bf16 v[88:91], v[196:199], v[64:67], 0
	v_mfma_f32_16x16x32_bf16 v[88:91], v[200:203], v[128:131], v[88:91]
	ds_read_b128 v[196:199], v169 offset:24576
	ds_read_b128 v[200:203], v170 offset:24576
	s_waitcnt lgkmcnt(4)
	v_mfma_f32_16x16x32_bf16 v[84:87], v[204:207], v[64:67], 0
	v_mfma_f32_16x16x32_bf16 v[84:87], v[208:211], v[128:131], v[84:87]
	ds_read_b128 v[204:207], v169 offset:26624
	ds_read_b128 v[208:211], v170 offset:26624
	s_waitcnt lgkmcnt(4)
	v_mfma_f32_16x16x32_bf16 v[76:79], v[212:215], v[64:67], 0
	v_mfma_f32_16x16x32_bf16 v[76:79], v[216:219], v[128:131], v[76:79]
	ds_read_b128 v[212:215], v169 offset:28672
	ds_read_b128 v[216:219], v170 offset:28672
	s_waitcnt lgkmcnt(4)
	v_mfma_f32_16x16x32_bf16 v[80:83], v[196:199], v[64:67], 0
	v_mfma_f32_16x16x32_bf16 v[80:83], v[200:203], v[128:131], v[80:83]
	ds_read_b128 v[196:199], v169 offset:30720
	ds_read_b128 v[200:203], v170 offset:30720
	s_waitcnt lgkmcnt(4)
	v_mfma_f32_16x16x32_bf16 v[72:75], v[204:207], v[64:67], 0
	v_mfma_f32_16x16x32_bf16 v[72:75], v[208:211], v[128:131], v[72:75]
	s_waitcnt lgkmcnt(2)
	v_mfma_f32_16x16x32_bf16 v[68:71], v[212:215], v[64:67], 0
	v_mfma_f32_16x16x32_bf16 v[68:71], v[216:219], v[128:131], v[68:71]
	s_waitcnt lgkmcnt(0)
	v_mfma_f32_16x16x32_bf16 v[64:67], v[196:199], v[64:67], 0
	v_mfma_f32_16x16x32_bf16 v[64:67], v[200:203], v[128:131], v[64:67]
	v_max_i32_e32 v128, 8, v189
	v_add_u32_e32 v128, -8, v128
	v_min_u32_e32 v190, 48, v128
	v_add_u32_e32 v192, v168, v138
	v_add_u32_e32 v191, 16, v190
	v_mov_b32_e32 v188, 0xf149f2ca
	v_cmp_ge_u32_e32 vcc, v192, v190
	v_cmp_lt_u32_e64 s[6:7], v192, v191
	v_sub_u32_e32 v194, v192, v189
	v_max_i32_e32 v194, -15, v194
	v_add_u32_e32 v194, 15, v194
	s_and_b64 s[8:9], vcc, s[6:7]
	v_min_u32_e32 v194, 30, v194
	v_lshl_add_u32 v196, v194, 2, s61
	v_add_u32_e32 v193, 1, v192
	v_cmp_ge_u32_e32 vcc, v193, v190
	v_cmp_lt_u32_e64 s[6:7], v193, v191
	v_sub_u32_e32 v194, v193, v189
	v_max_i32_e32 v194, -15, v194
	v_add_u32_e32 v194, 15, v194
	s_and_b64 s[10:11], vcc, s[6:7]
	v_min_u32_e32 v194, 30, v194
	v_lshl_add_u32 v197, v194, 2, s61
	v_add_u32_e32 v193, 2, v192
	v_cmp_ge_u32_e32 vcc, v193, v190
	v_cmp_lt_u32_e64 s[6:7], v193, v191
	v_sub_u32_e32 v194, v193, v189
	v_max_i32_e32 v194, -15, v194
	v_add_u32_e32 v194, 15, v194
	s_and_b64 s[22:23], vcc, s[6:7]
	v_min_u32_e32 v194, 30, v194
	v_lshl_add_u32 v198, v194, 2, s61
	v_add_u32_e32 v193, 3, v192
	v_cmp_ge_u32_e32 vcc, v193, v190
	v_cmp_lt_u32_e64 s[6:7], v193, v191
	v_sub_u32_e32 v194, v193, v189
	v_max_i32_e32 v194, -15, v194
	v_add_u32_e32 v194, 15, v194
	s_and_b64 s[28:29], vcc, s[6:7]
	v_min_u32_e32 v194, 30, v194
	v_lshl_add_u32 v199, v194, 2, s61
	v_add_u32_e32 v193, 16, v192
	v_cmp_ge_u32_e32 vcc, v193, v190
	v_cmp_lt_u32_e64 s[6:7], v193, v191
	v_sub_u32_e32 v194, v193, v189
	v_max_i32_e32 v194, -15, v194
	v_add_u32_e32 v194, 15, v194
	s_and_b64 s[44:45], vcc, s[6:7]
	v_min_u32_e32 v194, 30, v194
	v_lshl_add_u32 v200, v194, 2, s61
	v_add_u32_e32 v193, 17, v192
	v_cmp_ge_u32_e32 vcc, v193, v190
	v_cmp_lt_u32_e64 s[6:7], v193, v191
	v_sub_u32_e32 v194, v193, v189
	v_max_i32_e32 v194, -15, v194
	v_add_u32_e32 v194, 15, v194
	s_and_b64 s[48:49], vcc, s[6:7]
	v_min_u32_e32 v194, 30, v194
	v_lshl_add_u32 v201, v194, 2, s61
	v_add_u32_e32 v193, 18, v192
	v_cmp_ge_u32_e32 vcc, v193, v190
	v_cmp_lt_u32_e64 s[6:7], v193, v191
	v_sub_u32_e32 v194, v193, v189
	v_max_i32_e32 v194, -15, v194
	v_add_u32_e32 v194, 15, v194
	s_and_b64 s[50:51], vcc, s[6:7]
	v_min_u32_e32 v194, 30, v194
	v_lshl_add_u32 v202, v194, 2, s61
	v_add_u32_e32 v193, 19, v192
	v_cmp_ge_u32_e32 vcc, v193, v190
	v_cmp_lt_u32_e64 s[6:7], v193, v191
	v_sub_u32_e32 v194, v193, v189
	v_max_i32_e32 v194, -15, v194
	v_add_u32_e32 v194, 15, v194
	s_and_b64 s[98:99], vcc, s[6:7]
	v_min_u32_e32 v194, 30, v194
	v_lshl_add_u32 v203, v194, 2, s61
	ds_read_b32 v204, v196 offset:868
	ds_read_b32 v205, v197 offset:868
	ds_read_b32 v206, v198 offset:868
	ds_read_b32 v207, v199 offset:868
	ds_read_b32 v208, v200 offset:868
	ds_read_b32 v209, v201 offset:868
	ds_read_b32 v210, v202 offset:868
	ds_read_b32 v211, v203 offset:868
	ds_read_b32 v212, v196 offset:992
	ds_read_b32 v213, v197 offset:992
	ds_read_b32 v214, v198 offset:992
	ds_read_b32 v215, v199 offset:992
	ds_read_b32 v216, v200 offset:992
	ds_read_b32 v217, v201 offset:992
	ds_read_b32 v218, v202 offset:992
	ds_read_b32 v219, v203 offset:992
	s_waitcnt lgkmcnt(8)
	v_fmac_f32_e32 v204, 0x3e000000, v124
	v_cndmask_b32_e64 v129, v188, v204, s[8:9]
	v_fmac_f32_e32 v205, 0x3e000000, v125
	v_cndmask_b32_e64 v128, v188, v205, s[10:11]
	v_fmac_f32_e32 v206, 0x3e000000, v126
	v_cndmask_b32_e64 v125, v188, v206, s[22:23]
	v_fmac_f32_e32 v207, 0x3e000000, v127
	v_cndmask_b32_e64 v124, v188, v207, s[28:29]
	v_fmac_f32_e32 v208, 0x3e000000, v120
	v_cndmask_b32_e64 v127, v188, v208, s[44:45]
	v_fmac_f32_e32 v209, 0x3e000000, v121
	v_cndmask_b32_e64 v126, v188, v209, s[48:49]
	v_fmac_f32_e32 v210, 0x3e000000, v122
	v_cndmask_b32_e64 v121, v188, v210, s[50:51]
	v_fmac_f32_e32 v211, 0x3e000000, v123
	v_cndmask_b32_e64 v120, v188, v211, s[98:99]
	ds_read_b32 v204, v196 offset:1116
	ds_read_b32 v205, v197 offset:1116
	ds_read_b32 v206, v198 offset:1116
	ds_read_b32 v207, v199 offset:1116
	ds_read_b32 v208, v200 offset:1116
	ds_read_b32 v209, v201 offset:1116
	ds_read_b32 v210, v202 offset:1116
	ds_read_b32 v211, v203 offset:1116
	s_waitcnt lgkmcnt(8)
	v_fmac_f32_e32 v212, 0x3e000000, v116
	v_cndmask_b32_e64 v123, v188, v212, s[8:9]
	v_fmac_f32_e32 v213, 0x3e000000, v117
	v_cndmask_b32_e64 v122, v188, v213, s[10:11]
	v_fmac_f32_e32 v214, 0x3e000000, v118
	v_cndmask_b32_e64 v117, v188, v214, s[22:23]
	v_fmac_f32_e32 v215, 0x3e000000, v119
	v_cndmask_b32_e64 v116, v188, v215, s[28:29]
	v_fmac_f32_e32 v216, 0x3e000000, v112
	v_cndmask_b32_e64 v119, v188, v216, s[44:45]
	v_fmac_f32_e32 v217, 0x3e000000, v113
	v_cndmask_b32_e64 v118, v188, v217, s[48:49]
	v_fmac_f32_e32 v218, 0x3e000000, v114
	v_cndmask_b32_e64 v113, v188, v218, s[50:51]
	v_fmac_f32_e32 v219, 0x3e000000, v115
	v_cndmask_b32_e64 v112, v188, v219, s[98:99]
	ds_read_b32 v212, v196 offset:1240
	ds_read_b32 v213, v197 offset:1240
	ds_read_b32 v214, v198 offset:1240
	ds_read_b32 v215, v199 offset:1240
	ds_read_b32 v216, v200 offset:1240
	ds_read_b32 v217, v201 offset:1240
	ds_read_b32 v218, v202 offset:1240
	ds_read_b32 v219, v203 offset:1240
	s_waitcnt lgkmcnt(8)
	v_fmac_f32_e32 v204, 0x3e000000, v108
	v_cndmask_b32_e64 v115, v188, v204, s[8:9]
	v_fmac_f32_e32 v205, 0x3e000000, v109
	v_cndmask_b32_e64 v114, v188, v205, s[10:11]
	v_fmac_f32_e32 v206, 0x3e000000, v110
	v_cndmask_b32_e64 v109, v188, v206, s[22:23]
	v_fmac_f32_e32 v207, 0x3e000000, v111
	v_cndmask_b32_e64 v108, v188, v207, s[28:29]
	v_fmac_f32_e32 v208, 0x3e000000, v104
	v_cndmask_b32_e64 v111, v188, v208, s[44:45]
	v_fmac_f32_e32 v209, 0x3e000000, v105
	v_cndmask_b32_e64 v110, v188, v209, s[48:49]
	v_fmac_f32_e32 v210, 0x3e000000, v106
	v_cndmask_b32_e64 v105, v188, v210, s[50:51]
	v_fmac_f32_e32 v211, 0x3e000000, v107
	v_cndmask_b32_e64 v104, v188, v211, s[98:99]
	ds_read_b32 v204, v196 offset:1364
	ds_read_b32 v205, v197 offset:1364
	ds_read_b32 v206, v198 offset:1364
	ds_read_b32 v207, v199 offset:1364
	ds_read_b32 v208, v200 offset:1364
	ds_read_b32 v209, v201 offset:1364
	ds_read_b32 v210, v202 offset:1364
	ds_read_b32 v211, v203 offset:1364
	s_waitcnt lgkmcnt(8)
	v_fmac_f32_e32 v212, 0x3e000000, v100
	v_cndmask_b32_e64 v107, v188, v212, s[8:9]
	v_fmac_f32_e32 v213, 0x3e000000, v101
	v_cndmask_b32_e64 v106, v188, v213, s[10:11]
	v_fmac_f32_e32 v214, 0x3e000000, v102
	v_cndmask_b32_e64 v101, v188, v214, s[22:23]
	v_fmac_f32_e32 v215, 0x3e000000, v103
	v_cndmask_b32_e64 v100, v188, v215, s[28:29]
	v_fmac_f32_e32 v216, 0x3e000000, v96
	v_cndmask_b32_e64 v103, v188, v216, s[44:45]
	v_fmac_f32_e32 v217, 0x3e000000, v97
	v_cndmask_b32_e64 v102, v188, v217, s[48:49]
	v_fmac_f32_e32 v218, 0x3e000000, v98
	v_cndmask_b32_e64 v97, v188, v218, s[50:51]
	v_fmac_f32_e32 v219, 0x3e000000, v99
	v_cndmask_b32_e64 v96, v188, v219, s[98:99]
	ds_read_b32 v212, v196 offset:1488
	ds_read_b32 v213, v197 offset:1488
	ds_read_b32 v214, v198 offset:1488
	ds_read_b32 v215, v199 offset:1488
	ds_read_b32 v216, v200 offset:1488
	ds_read_b32 v217, v201 offset:1488
	ds_read_b32 v218, v202 offset:1488
	ds_read_b32 v219, v203 offset:1488
	s_waitcnt lgkmcnt(8)
	v_fmac_f32_e32 v204, 0x3e000000, v92
	v_cndmask_b32_e64 v99, v188, v204, s[8:9]
	v_fmac_f32_e32 v205, 0x3e000000, v93
	v_cndmask_b32_e64 v98, v188, v205, s[10:11]
	v_fmac_f32_e32 v206, 0x3e000000, v94
	v_cndmask_b32_e64 v93, v188, v206, s[22:23]
	v_fmac_f32_e32 v207, 0x3e000000, v95
	v_cndmask_b32_e64 v92, v188, v207, s[28:29]
	v_fmac_f32_e32 v208, 0x3e000000, v88
	v_cndmask_b32_e64 v95, v188, v208, s[44:45]
	v_fmac_f32_e32 v209, 0x3e000000, v89
	v_cndmask_b32_e64 v94, v188, v209, s[48:49]
	v_fmac_f32_e32 v210, 0x3e000000, v90
	v_cndmask_b32_e64 v89, v188, v210, s[50:51]
	v_fmac_f32_e32 v211, 0x3e000000, v91
	v_cndmask_b32_e64 v88, v188, v211, s[98:99]
	ds_read_b32 v204, v196 offset:1612
	ds_read_b32 v205, v197 offset:1612
	ds_read_b32 v206, v198 offset:1612
	ds_read_b32 v207, v199 offset:1612
	ds_read_b32 v208, v200 offset:1612
	ds_read_b32 v209, v201 offset:1612
	ds_read_b32 v210, v202 offset:1612
	ds_read_b32 v211, v203 offset:1612
	s_waitcnt lgkmcnt(8)
	v_fmac_f32_e32 v212, 0x3e000000, v84
	v_cndmask_b32_e64 v91, v188, v212, s[8:9]
	v_fmac_f32_e32 v213, 0x3e000000, v85
	v_cndmask_b32_e64 v90, v188, v213, s[10:11]
	v_fmac_f32_e32 v214, 0x3e000000, v86
	v_cndmask_b32_e64 v85, v188, v214, s[22:23]
	v_fmac_f32_e32 v215, 0x3e000000, v87
	v_cndmask_b32_e64 v84, v188, v215, s[28:29]
	v_fmac_f32_e32 v216, 0x3e000000, v76
	v_cndmask_b32_e64 v87, v188, v216, s[44:45]
	v_fmac_f32_e32 v217, 0x3e000000, v77
	v_cndmask_b32_e64 v86, v188, v217, s[48:49]
	v_fmac_f32_e32 v218, 0x3e000000, v78
	v_cndmask_b32_e64 v77, v188, v218, s[50:51]
	v_fmac_f32_e32 v219, 0x3e000000, v79
	v_cndmask_b32_e64 v76, v188, v219, s[98:99]
	ds_read_b32 v212, v196 offset:1736
	ds_read_b32 v213, v197 offset:1736
	ds_read_b32 v214, v198 offset:1736
	ds_read_b32 v215, v199 offset:1736
	ds_read_b32 v216, v200 offset:1736
	ds_read_b32 v217, v201 offset:1736
	ds_read_b32 v218, v202 offset:1736
	ds_read_b32 v219, v203 offset:1736
	s_waitcnt lgkmcnt(8)
	v_fmac_f32_e32 v204, 0x3e000000, v80
	v_cndmask_b32_e64 v79, v188, v204, s[8:9]
	v_fmac_f32_e32 v205, 0x3e000000, v81
	v_cndmask_b32_e64 v78, v188, v205, s[10:11]
	v_fmac_f32_e32 v206, 0x3e000000, v82
	v_cndmask_b32_e64 v81, v188, v206, s[22:23]
	v_fmac_f32_e32 v207, 0x3e000000, v83
	v_cndmask_b32_e64 v80, v188, v207, s[28:29]
	v_fmac_f32_e32 v208, 0x3e000000, v72
	v_cndmask_b32_e64 v83, v188, v208, s[44:45]
	v_fmac_f32_e32 v209, 0x3e000000, v73
	v_cndmask_b32_e64 v82, v188, v209, s[48:49]
	v_fmac_f32_e32 v210, 0x3e000000, v74
	v_cndmask_b32_e64 v73, v188, v210, s[50:51]
	v_fmac_f32_e32 v211, 0x3e000000, v75
	v_cndmask_b32_e64 v72, v188, v211, s[98:99]
	s_waitcnt lgkmcnt(0)
	v_fmac_f32_e32 v212, 0x3e000000, v68
	v_cndmask_b32_e64 v75, v188, v212, s[8:9]
	v_fmac_f32_e32 v213, 0x3e000000, v69
	v_cndmask_b32_e64 v74, v188, v213, s[10:11]
	v_fmac_f32_e32 v214, 0x3e000000, v70
	v_cndmask_b32_e64 v69, v188, v214, s[22:23]
	v_fmac_f32_e32 v215, 0x3e000000, v71
	v_cndmask_b32_e64 v68, v188, v215, s[28:29]
	v_fmac_f32_e32 v216, 0x3e000000, v64
	v_cndmask_b32_e64 v71, v188, v216, s[44:45]
	v_fmac_f32_e32 v217, 0x3e000000, v65
	v_cndmask_b32_e64 v70, v188, v217, s[48:49]
	v_fmac_f32_e32 v218, 0x3e000000, v66
	v_cndmask_b32_e64 v65, v188, v218, s[50:51]
	v_fmac_f32_e32 v219, 0x3e000000, v67
	v_cndmask_b32_e64 v64, v188, v219, s[98:99]
	s_mov_b32 s6, 0xff61b1e6
	v_max3_f32 v66, v129, s6, v128
	v_max3_f32 v66, v66, v125, v124
	v_max3_f32 v66, v66, v127, v126
	v_max3_f32 v66, v66, v121, v120
	v_max3_f32 v66, v66, v123, v122
	v_max3_f32 v66, v66, v117, v116
	v_max3_f32 v66, v66, v119, v118
	v_max3_f32 v66, v66, v113, v112
	v_max3_f32 v66, v66, v115, v114
	v_max3_f32 v66, v66, v109, v108
	v_max3_f32 v66, v66, v111, v110
	v_max3_f32 v66, v66, v105, v104
	v_max3_f32 v66, v66, v107, v106
	v_max3_f32 v66, v66, v101, v100
	v_max3_f32 v66, v66, v103, v102
	v_max3_f32 v66, v66, v97, v96
	v_max3_f32 v66, v66, v99, v98
	v_max3_f32 v66, v66, v93, v92
	v_max3_f32 v66, v66, v95, v94
	v_max3_f32 v66, v66, v89, v88
	v_max3_f32 v66, v66, v91, v90
	v_max3_f32 v66, v66, v85, v84
	v_max3_f32 v66, v66, v87, v86
	v_max3_f32 v66, v66, v77, v76
	v_max3_f32 v66, v66, v79, v78
	v_max3_f32 v66, v66, v81, v80
	v_max3_f32 v66, v66, v83, v82
	v_max3_f32 v66, v66, v73, v72
	v_max3_f32 v66, v66, v75, v74
	v_max3_f32 v66, v66, v69, v68
	v_max3_f32 v66, v66, v71, v70
	v_max3_f32 v66, v66, v65, v64
	ds_bpermute_b32 v67, v163, v66
	s_waitcnt lgkmcnt(0)
	v_max_f32_e32 v67, v67, v67
	v_max_f32_e32 v66, v66, v67
	ds_bpermute_b32 v67, v164, v66
	s_waitcnt lgkmcnt(0)
	v_max_f32_e32 v67, v67, v67
	v_max_f32_e32 v66, v66, v67
	v_mul_f32_e32 v216, 0xbfb8aa3b, v66
	v_fmamk_f32 v67, v129, 0x3fb8aa3b, v216
	v_fmamk_f32 v128, v128, 0x3fb8aa3b, v216
	v_exp_f32_e32 v67, v67
	v_fmamk_f32 v125, v125, 0x3fb8aa3b, v216
	v_exp_f32_e32 v128, v128
	v_fmamk_f32 v124, v124, 0x3fb8aa3b, v216
	v_exp_f32_e32 v125, v125
	v_fmamk_f32 v127, v127, 0x3fb8aa3b, v216
	v_exp_f32_e32 v124, v124
	v_add_f32_e32 v129, 0, v67
	v_exp_f32_e32 v127, v127
	v_fmamk_f32 v126, v126, 0x3fb8aa3b, v216
	v_add_f32_e32 v129, v128, v129
	v_exp_f32_e32 v126, v126
	v_fmamk_f32 v121, v121, 0x3fb8aa3b, v216
	v_add_f32_e32 v129, v125, v129
	v_exp_f32_e32 v121, v121
	v_fmamk_f32 v120, v120, 0x3fb8aa3b, v216
	v_add_f32_e32 v129, v124, v129
	v_exp_f32_e32 v120, v120
	v_fmamk_f32 v123, v123, 0x3fb8aa3b, v216
	v_add_f32_e32 v129, v127, v129
	v_exp_f32_e32 v123, v123
	v_fmamk_f32 v122, v122, 0x3fb8aa3b, v216
	v_add_f32_e32 v129, v126, v129
	v_exp_f32_e32 v122, v122
	v_fmamk_f32 v117, v117, 0x3fb8aa3b, v216
	v_add_f32_e32 v129, v121, v129
	v_exp_f32_e32 v117, v117
	v_fmamk_f32 v116, v116, 0x3fb8aa3b, v216
	v_add_f32_e32 v129, v120, v129
	v_exp_f32_e32 v116, v116
	v_fmamk_f32 v119, v119, 0x3fb8aa3b, v216
	v_add_f32_e32 v129, v123, v129
	v_exp_f32_e32 v119, v119
	v_fmamk_f32 v118, v118, 0x3fb8aa3b, v216
	v_add_f32_e32 v129, v122, v129
	v_exp_f32_e32 v118, v118
	v_fmamk_f32 v113, v113, 0x3fb8aa3b, v216
	v_add_f32_e32 v129, v117, v129
	v_exp_f32_e32 v113, v113
	v_fmamk_f32 v112, v112, 0x3fb8aa3b, v216
	v_add_f32_e32 v129, v116, v129
	v_exp_f32_e32 v112, v112
	v_fmamk_f32 v115, v115, 0x3fb8aa3b, v216
	v_add_f32_e32 v129, v119, v129
	v_exp_f32_e32 v115, v115
	v_fmamk_f32 v114, v114, 0x3fb8aa3b, v216
	v_add_f32_e32 v129, v118, v129
	v_exp_f32_e32 v114, v114
	v_fmamk_f32 v109, v109, 0x3fb8aa3b, v216
	v_add_f32_e32 v129, v113, v129
	v_exp_f32_e32 v109, v109
	v_fmamk_f32 v108, v108, 0x3fb8aa3b, v216
	v_add_f32_e32 v129, v112, v129
	v_exp_f32_e32 v108, v108
	v_fmamk_f32 v111, v111, 0x3fb8aa3b, v216
	v_add_f32_e32 v129, v115, v129
	v_exp_f32_e32 v111, v111
	v_fmamk_f32 v110, v110, 0x3fb8aa3b, v216
	v_add_f32_e32 v129, v114, v129
	v_exp_f32_e32 v110, v110
	v_fmamk_f32 v105, v105, 0x3fb8aa3b, v216
	v_add_f32_e32 v129, v109, v129
	v_exp_f32_e32 v105, v105
	v_fmamk_f32 v104, v104, 0x3fb8aa3b, v216
	v_add_f32_e32 v129, v108, v129
	v_exp_f32_e32 v104, v104
	v_fmamk_f32 v107, v107, 0x3fb8aa3b, v216
	v_add_f32_e32 v129, v111, v129
	v_exp_f32_e32 v107, v107
	v_fmamk_f32 v106, v106, 0x3fb8aa3b, v216
	v_add_f32_e32 v129, v110, v129
	v_exp_f32_e32 v106, v106
	v_fmamk_f32 v101, v101, 0x3fb8aa3b, v216
	v_add_f32_e32 v129, v105, v129
	v_exp_f32_e32 v101, v101
	v_fmamk_f32 v100, v100, 0x3fb8aa3b, v216
	v_add_f32_e32 v129, v104, v129
	v_exp_f32_e32 v100, v100
	v_fmamk_f32 v103, v103, 0x3fb8aa3b, v216
	v_add_f32_e32 v129, v107, v129
	v_exp_f32_e32 v103, v103
	v_fmamk_f32 v102, v102, 0x3fb8aa3b, v216
	v_fmamk_f32 v97, v97, 0x3fb8aa3b, v216
	v_add_f32_e32 v129, v106, v129
	v_exp_f32_e32 v102, v102
	v_exp_f32_e32 v130, v97
	v_add_f32_e32 v129, v101, v129
	v_fmamk_f32 v96, v96, 0x3fb8aa3b, v216
	v_fmamk_f32 v97, v99, 0x3fb8aa3b, v216
	v_add_f32_e32 v129, v100, v129
	v_exp_f32_e32 v131, v96
	v_exp_f32_e32 v99, v97
	v_add_f32_e32 v96, v103, v129
	v_fmamk_f32 v97, v98, 0x3fb8aa3b, v216
	v_fmamk_f32 v93, v93, 0x3fb8aa3b, v216
	v_add_f32_e32 v96, v102, v96
	v_exp_f32_e32 v98, v97
	v_exp_f32_e32 v129, v93
	v_add_f32_e32 v96, v130, v96
	v_fmamk_f32 v92, v92, 0x3fb8aa3b, v216
	v_fmamk_f32 v93, v95, 0x3fb8aa3b, v216
	v_add_f32_e32 v96, v131, v96
	v_exp_f32_e32 v168, v92
	v_exp_f32_e32 v169, v93
	v_add_f32_e32 v92, v99, v96
	v_fmamk_f32 v93, v94, 0x3fb8aa3b, v216
	v_fmamk_f32 v89, v89, 0x3fb8aa3b, v216
	v_add_f32_e32 v92, v98, v92
	v_exp_f32_e32 v170, v93
	v_exp_f32_e32 v171, v89
	v_add_f32_e32 v92, v129, v92
	v_fmamk_f32 v88, v88, 0x3fb8aa3b, v216
	v_fmamk_f32 v89, v91, 0x3fb8aa3b, v216
	v_add_f32_e32 v92, v168, v92
	v_exp_f32_e32 v188, v88
	v_exp_f32_e32 v189, v89
	v_add_f32_e32 v88, v169, v92
	v_fmamk_f32 v89, v90, 0x3fb8aa3b, v216
	v_fmamk_f32 v85, v85, 0x3fb8aa3b, v216
	v_fmamk_f32 v77, v77, 0x3fb8aa3b, v216
	v_add_f32_e32 v88, v170, v88
	v_exp_f32_e32 v190, v89
	v_exp_f32_e32 v191, v85
	v_exp_f32_e32 v195, v77
	v_add_f32_e32 v88, v171, v88
	v_fmamk_f32 v84, v84, 0x3fb8aa3b, v216
	v_fmamk_f32 v85, v87, 0x3fb8aa3b, v216
	v_fmamk_f32 v77, v79, 0x3fb8aa3b, v216
	v_add_f32_e32 v88, v188, v88
	v_exp_f32_e32 v192, v84
	v_exp_f32_e32 v193, v85
	v_exp_f32_e32 v197, v77
	v_add_f32_e32 v84, v189, v88
	v_fmamk_f32 v85, v86, 0x3fb8aa3b, v216
	v_fmamk_f32 v77, v78, 0x3fb8aa3b, v216
	v_add_f32_e32 v84, v190, v84
	v_exp_f32_e32 v194, v85
	v_exp_f32_e32 v198, v77
	v_add_f32_e32 v84, v191, v84
	v_fmamk_f32 v76, v76, 0x3fb8aa3b, v216
	v_fmamk_f32 v77, v81, 0x3fb8aa3b, v216
	v_add_f32_e32 v84, v192, v84
	v_exp_f32_e32 v196, v76
	v_exp_f32_e32 v199, v77
	v_add_f32_e32 v76, v193, v84
	v_fmamk_f32 v77, v80, 0x3fb8aa3b, v216
	v_add_f32_e32 v76, v194, v76
	v_exp_f32_e32 v200, v77
	v_add_f32_e32 v76, v195, v76
	v_fmamk_f32 v77, v83, 0x3fb8aa3b, v216
	v_add_f32_e32 v76, v196, v76
	v_exp_f32_e32 v201, v77
	v_add_f32_e32 v76, v197, v76
	v_fmamk_f32 v77, v82, 0x3fb8aa3b, v216
	v_fmamk_f32 v73, v73, 0x3fb8aa3b, v216
	v_add_f32_e32 v76, v198, v76
	v_exp_f32_e32 v202, v77
	v_exp_f32_e32 v203, v73
	v_add_f32_e32 v76, v199, v76
	v_fmamk_f32 v72, v72, 0x3fb8aa3b, v216
	v_fmamk_f32 v73, v75, 0x3fb8aa3b, v216
	v_add_f32_e32 v76, v200, v76
	v_exp_f32_e32 v204, v72
	v_exp_f32_e32 v205, v73
	v_add_f32_e32 v72, v201, v76
	v_fmamk_f32 v73, v74, 0x3fb8aa3b, v216
	v_fmamk_f32 v69, v69, 0x3fb8aa3b, v216
	v_add_f32_e32 v72, v202, v72
	v_exp_f32_e32 v206, v73
	v_exp_f32_e32 v207, v69
	v_add_f32_e32 v72, v203, v72
	v_fmamk_f32 v68, v68, 0x3fb8aa3b, v216
	v_fmamk_f32 v69, v71, 0x3fb8aa3b, v216
	v_add_f32_e32 v72, v204, v72
	v_exp_f32_e32 v208, v68
	v_exp_f32_e32 v209, v69
	v_add_f32_e32 v68, v205, v72
	v_fmamk_f32 v69, v70, 0x3fb8aa3b, v216
	v_add_f32_e32 v68, v206, v68
	v_exp_f32_e32 v210, v69
	v_fmamk_f32 v65, v65, 0x3fb8aa3b, v216
	v_add_f32_e32 v68, v207, v68
	v_exp_f32_e32 v211, v65
	v_fmamk_f32 v64, v64, 0x3fb8aa3b, v216
	v_add_f32_e32 v68, v208, v68
	v_exp_f32_e32 v212, v64
	v_add_f32_e32 v64, v209, v68
	v_add_f32_e32 v64, v210, v64
	v_add_f32_e32 v64, v211, v64
	v_add_f32_e32 v64, v212, v64
	ds_bpermute_b32 v65, v163, v64
	v_cvt_pk_bf16_f32 v92, v67, v128
	v_cvt_pk_bf16_f32 v93, v125, v124
	v_cvt_pk_bf16_f32 v94, v127, v126
	v_cvt_pk_bf16_f32 v95, v121, v120
	s_waitcnt lgkmcnt(0)
	v_add_f32_e32 v96, v64, v65
	ds_bpermute_b32 v97, v164, v96
	v_cvt_pk_bf16_f32 v88, v123, v122
	v_cvt_pk_bf16_f32 v89, v117, v116
	v_cvt_pk_bf16_f32 v90, v119, v118
	v_cvt_pk_bf16_f32 v91, v113, v112
	v_cvt_pk_bf16_f32 v84, v115, v114
	v_cvt_pk_bf16_f32 v85, v109, v108
	v_cvt_pk_bf16_f32 v86, v111, v110
	v_cvt_pk_bf16_f32 v87, v105, v104
	v_cvt_pk_bf16_f32 v80, v107, v106
	v_cvt_pk_bf16_f32 v81, v101, v100
	v_cvt_pk_bf16_f32 v82, v103, v102
	v_cvt_pk_bf16_f32 v83, v130, v131
	v_cvt_pk_bf16_f32 v76, v99, v98
	v_cvt_pk_bf16_f32 v77, v129, v168
	v_cvt_pk_bf16_f32 v78, v169, v170
	v_cvt_pk_bf16_f32 v79, v171, v188
	v_cvt_pk_bf16_f32 v72, v189, v190
	v_cvt_pk_bf16_f32 v73, v191, v192
	v_cvt_pk_bf16_f32 v74, v193, v194
	v_cvt_pk_bf16_f32 v75, v195, v196
	v_cvt_pk_bf16_f32 v68, v197, v198
	v_cvt_pk_bf16_f32 v69, v199, v200
	v_cvt_pk_bf16_f32 v70, v201, v202
	v_cvt_pk_bf16_f32 v71, v203, v204
	v_cvt_pk_bf16_f32 v64, v205, v206
	v_cvt_pk_bf16_f32 v65, v207, v208
	v_cvt_pk_bf16_f32 v66, v209, v210
	v_cvt_pk_bf16_f32 v67, v211, v212
	v_cndmask_b32_e64 v98, 0, 1, s[4:5]
	v_cmp_ne_u32_e64 s[44:45], 1, v98
	s_andn2_b64 vcc, exec, s[4:5]
	s_mov_b64 s[4:5], -1
	s_cbranch_vccnz .LBB0_635
	v_readlane_b32 s4, v250, 13
	s_add_i32 s6, s59, s4
	s_mov_b64 s[4:5], 0
